# post-projection head-norm reductions (xor 1,2,4) via DPP adds instead of ds_bpermute round trips, 4 chains (on top of v42)
# baseline (speedup 1.0000x reference)
.LBB0_334:
	s_or_b64 exec, exec, s[0:1]
	v_lshlrev_b32_e32 v130, 4, v130
	v_ashrrev_i32_e32 v131, 31, v130
	v_lshl_add_u64 v[138:139], v[130:131], 2, v[150:151]
	s_mov_b64 s[0:1], 0x2000
	v_lshl_add_u64 v[140:141], v[138:139], 0, s[0:1]
	s_movk_i32 s0, 0x2000
	global_load_dwordx4 v[134:137], v[138:139], off
	global_load_dwordx4 v[130:133], v[138:139], off offset:16
	v_add_co_u32_e32 v138, vcc, s0, v138
	s_waitcnt vmcnt(5)
	v_lshlrev_b32_e32 v164, 16, v146
	v_addc_co_u32_e32 v139, vcc, 0, v139, vcc
	global_load_dwordx4 v[142:145], v[138:139], off
	s_nop 0
	global_load_dwordx4 v[138:141], v[140:141], off offset:16
	v_and_b32_e32 v165, 0xffff0000, v146
	v_lshlrev_b32_e32 v160, 16, v147
	v_and_b32_e32 v161, 0xffff0000, v147
	v_pk_mul_f32 v[146:147], v[164:165], v[164:165]
	v_pk_mul_f32 v[162:163], v[160:161], v[160:161]
	v_add_f32_e32 v146, v146, v147
	v_lshlrev_b32_e32 v158, 16, v148
	v_and_b32_e32 v159, 0xffff0000, v148
	v_add_f32_e32 v146, v162, v146
	v_lshlrev_b32_e32 v154, 16, v149
	v_and_b32_e32 v155, 0xffff0000, v149
	v_pk_mul_f32 v[148:149], v[158:159], v[158:159]
	v_add_f32_e32 v146, v163, v146
	v_add_f32_e32 v146, v148, v146
	v_pk_mul_f32 v[156:157], v[154:155], v[154:155]
	v_add_f32_e32 v146, v149, v146
	v_add_f32_e32 v146, v156, v146
	v_add_f32_e32 v146, v157, v146
	s_waitcnt lgkmcnt(0)
	s_nop 1
	v_add_f32_dpp v146, v146, v146 quad_perm:[1,0,3,2] row_mask:0xf bank_mask:0xf
	s_nop 1
	v_add_f32_dpp v146, v146, v146 quad_perm:[2,3,0,1] row_mask:0xf bank_mask:0xf
	s_nop 1
	v_add_f32_dpp v146, v146, v146 row_half_mirror row_mask:0xf bank_mask:0xf
	s_nop 1
	v_fmamk_f32 v146, v146, 0x3c800000, v199
	v_cmp_gt_f32_e32 vcc, s21, v146
	v_mul_f32_e32 v147, 0x4f800000, v146
	s_nop 0
	v_cndmask_b32_e32 v146, v146, v147, vcc
	v_sqrt_f32_e32 v147, v146
	s_nop 0
	v_add_u32_e32 v148, -1, v147
	v_fma_f32 v149, -v148, v147, v146
	v_cmp_ge_f32_e64 s[50:51], 0, v149
	v_add_u32_e32 v149, 1, v147
	s_nop 0
	v_cndmask_b32_e64 v148, v147, v148, s[50:51]
	v_fma_f32 v147, -v149, v147, v146
	v_cmp_lt_f32_e64 s[50:51], 0, v147
	s_nop 1
	v_cndmask_b32_e64 v147, v148, v149, s[50:51]
	v_mul_f32_e32 v148, 0x37800000, v147
	v_cndmask_b32_e32 v147, v147, v148, vcc
	v_cmp_class_f32_e32 vcc, v146, v200
	s_nop 1
	v_cndmask_b32_e32 v146, v147, v146, vcc
	v_div_scale_f32 v147, s[0:1], v146, v146, 1.0
	v_rcp_f32_e32 v148, v147
	s_nop 0
	v_fma_f32 v149, -v147, v148, 1.0
	v_fmac_f32_e32 v148, v149, v148
	v_div_scale_f32 v149, vcc, 1.0, v146, 1.0
	v_mul_f32_e32 v156, v149, v148
	v_fma_f32 v157, -v147, v156, v149
	v_fmac_f32_e32 v156, v157, v148
	v_fma_f32 v147, -v147, v156, v149
	v_div_fmas_f32 v147, v147, v148, v156
	v_div_fixup_f32 v146, v147, v146, 1.0
	v_pk_mul_f32 v[148:149], v[146:147], v[164:165] op_sel_hi:[0,1]
	v_pk_mul_f32 v[148:149], v[14:15], v[148:149]
	v_pk_mul_f32 v[156:157], v[146:147], v[160:161] op_sel_hi:[0,1]
	v_pk_mul_f32 v[158:159], v[146:147], v[158:159] op_sel_hi:[0,1]
	v_pk_mul_f32 v[146:147], v[146:147], v[154:155] op_sel_hi:[0,1]
	ds_bpermute_b32 v154, v177, v148
	ds_bpermute_b32 v155, v177, v149
	v_pk_mul_f32 v[156:157], v[16:17], v[156:157]
	v_pk_mul_f32 v[158:159], v[10:11], v[158:159]
	v_pk_mul_f32 v[146:147], v[12:13], v[146:147]
	s_waitcnt vmcnt(1) lgkmcnt(0)
	v_pk_mul_f32 v[154:155], v[142:143], v[154:155]
	s_nop 0
	v_cndmask_b32_e64 v155, v155, -v155, s[44:45]
	v_cndmask_b32_e64 v154, v154, -v154, s[44:45]
	v_pk_fma_f32 v[148:149], v[134:135], v[148:149], v[154:155]
	ds_bpermute_b32 v154, v177, v156
	ds_bpermute_b32 v155, v177, v157
	v_pk_mul_f32 v[148:149], v[148:149], s[20:21] op_sel_hi:[1,0]
	s_waitcnt lgkmcnt(0)
	v_pk_mul_f32 v[154:155], v[144:145], v[154:155]
	s_nop 0
	v_cndmask_b32_e64 v155, v155, -v155, s[44:45]
	v_cndmask_b32_e64 v154, v154, -v154, s[44:45]
	v_pk_fma_f32 v[154:155], v[136:137], v[156:157], v[154:155]
	ds_bpermute_b32 v156, v177, v158
	ds_bpermute_b32 v157, v177, v159
	v_pk_mul_f32 v[154:155], v[154:155], s[20:21] op_sel_hi:[1,0]
	s_waitcnt vmcnt(0) lgkmcnt(0)
	s_mov_b64 s[0:1], 0xc302000
	v_lshl_add_u64 v[192:193], s[16:17], 0, v[0:1]
	s_nop 0
	v_lshl_add_u64 v[192:193], v[192:193], 0, s[0:1]
	global_load_dwordx4 v[182:185], v[192:193], off offset:-3584
	global_load_dwordx4 v[182:185], v[192:193], off offset:-512
	global_load_dwordx4 v[182:185], v[192:193], off offset:512
	global_load_dwordx4 v[182:185], v[192:193], off offset:2048
	global_load_dwordx4 v[182:185], v[192:193], off offset:3072
	v_pk_mul_f32 v[156:157], v[138:139], v[156:157]
	s_nop 0
	v_cndmask_b32_e64 v157, v157, -v157, s[44:45]
	v_cndmask_b32_e64 v156, v156, -v156, s[44:45]
	v_pk_fma_f32 v[156:157], v[130:131], v[158:159], v[156:157]
	ds_bpermute_b32 v158, v177, v146
	ds_bpermute_b32 v159, v177, v147
	v_pk_mul_f32 v[156:157], v[156:157], s[20:21] op_sel_hi:[1,0]
	s_waitcnt lgkmcnt(0)
	v_pk_mul_f32 v[158:159], v[140:141], v[158:159]
	s_nop 0
	v_cndmask_b32_e64 v159, v159, -v159, s[44:45]
	v_cndmask_b32_e64 v158, v158, -v158, s[44:45]
	v_pk_fma_f32 v[146:147], v[132:133], v[146:147], v[158:159]
	s_nop 0
	v_pk_mul_f32 v[158:159], v[146:147], s[20:21] op_sel_hi:[1,0]
	v_cvt_pk_bf16_f32 v146, v148, v149
	v_cvt_pk_bf16_f32 v147, v154, v155
	v_cvt_pk_bf16_f32 v148, v156, v157
	v_cvt_pk_bf16_f32 v149, v158, v159
	v_lshl_add_u64 v[154:155], s[10:11], 0, v[0:1]
	v_lshlrev_b32_e32 v156, 16, v126
	v_and_b32_e32 v157, 0xffff0000, v126
	global_store_dwordx4 v[154:155], v[146:149], off
	v_lshlrev_b32_e32 v154, 16, v127
	v_and_b32_e32 v155, 0xffff0000, v127
	v_pk_mul_f32 v[164:165], v[156:157], v[156:157]
	v_pk_mul_f32 v[158:159], v[154:155], v[154:155]
	v_add_f32_e32 v164, v164, v165
	v_lshlrev_b32_e32 v148, 16, v128
	v_and_b32_e32 v149, 0xffff0000, v128
	v_add_f32_e32 v158, v158, v164
	v_pk_mul_f32 v[160:161], v[148:149], v[148:149]
	v_add_f32_e32 v158, v159, v158
	v_lshlrev_b32_e32 v146, 16, v129
	v_and_b32_e32 v147, 0xffff0000, v129
	v_add_f32_e32 v158, v160, v158
	v_pk_mul_f32 v[162:163], v[146:147], v[146:147]
	v_add_f32_e32 v158, v161, v158
	v_add_f32_e32 v158, v162, v158
	v_add_f32_e32 v158, v163, v158
	s_waitcnt lgkmcnt(0)
	s_nop 1
	v_add_f32_dpp v158, v158, v158 quad_perm:[1,0,3,2] row_mask:0xf bank_mask:0xf
	s_nop 1
	v_add_f32_dpp v158, v158, v158 quad_perm:[2,3,0,1] row_mask:0xf bank_mask:0xf
	s_nop 1
	v_add_f32_dpp v158, v158, v158 row_half_mirror row_mask:0xf bank_mask:0xf
	s_nop 1
	v_fmamk_f32 v158, v158, 0x3c800000, v199
	v_cmp_gt_f32_e32 vcc, s21, v158
	v_mul_f32_e32 v159, 0x4f800000, v158
	s_nop 0
	v_cndmask_b32_e32 v158, v158, v159, vcc
	v_sqrt_f32_e32 v159, v158
	s_nop 0
	v_add_u32_e32 v160, -1, v159
	v_fma_f32 v161, -v160, v159, v158
	v_cmp_ge_f32_e64 s[50:51], 0, v161
	v_add_u32_e32 v161, 1, v159
	s_nop 0
	v_cndmask_b32_e64 v160, v159, v160, s[50:51]
	v_fma_f32 v159, -v161, v159, v158
	v_cmp_lt_f32_e64 s[50:51], 0, v159
	s_nop 1
	v_cndmask_b32_e64 v159, v160, v161, s[50:51]
	v_mul_f32_e32 v160, 0x37800000, v159
	v_cndmask_b32_e32 v159, v159, v160, vcc
	v_cmp_class_f32_e32 vcc, v158, v200
	s_nop 1
	v_cndmask_b32_e32 v158, v159, v158, vcc
	v_div_scale_f32 v159, s[0:1], v158, v158, 1.0
	v_rcp_f32_e32 v160, v159
	s_nop 0
	v_fma_f32 v161, -v159, v160, 1.0
	v_fmac_f32_e32 v160, v161, v160
	v_div_scale_f32 v161, vcc, 1.0, v158, 1.0
	v_mul_f32_e32 v162, v161, v160
	v_fma_f32 v163, -v159, v162, v161
	v_fmac_f32_e32 v162, v163, v160
	v_fma_f32 v159, -v159, v162, v161
	v_div_fmas_f32 v159, v159, v160, v162
	v_div_fixup_f32 v158, v159, v158, 1.0
	v_pk_mul_f32 v[160:161], v[158:159], v[156:157] op_sel_hi:[0,1]
	v_pk_mul_f32 v[164:165], v[22:23], v[160:161]
	v_pk_mul_f32 v[160:161], v[158:159], v[154:155] op_sel_hi:[0,1]
	v_pk_mul_f32 v[162:163], v[24:25], v[160:161]
	v_pk_mul_f32 v[160:161], v[158:159], v[148:149] op_sel_hi:[0,1]
	v_pk_mul_f32 v[158:159], v[158:159], v[146:147] op_sel_hi:[0,1]
	v_pk_mul_f32 v[160:161], v[18:19], v[160:161]
	v_pk_mul_f32 v[158:159], v[20:21], v[158:159]
	ds_bpermute_b32 v172, v177, v164
	ds_bpermute_b32 v173, v177, v165
	ds_bpermute_b32 v170, v177, v162
	ds_bpermute_b32 v171, v177, v163
	ds_bpermute_b32 v168, v177, v160
	ds_bpermute_b32 v169, v177, v161
	ds_bpermute_b32 v166, v177, v158
	ds_bpermute_b32 v167, v177, v159
	s_and_saveexec_b64 s[0:1], s[46:47]
	s_xor_b64 s[0:1], exec, s[0:1]
	s_cbranch_execz .LBB0_338
	s_and_saveexec_b64 s[22:23], s[48:49]
	s_cbranch_execz .LBB0_337
	v_lshl_add_u64 v[130:131], s[4:5], 0, v[0:1]
	v_add_co_u32_e32 v130, vcc, 0x1326f000, v130
	s_nop 1
	v_addc_co_u32_e32 v131, vcc, 0, v131, vcc
	global_store_dwordx4 v[130:131], v[126:129], off offset:3840

.LBB0_340:
	s_or_b64 exec, exec, s[0:1]
	s_nop 0
	v_lshlrev_b32_e32 v128, 16, v122
	v_and_b32_e32 v129, 0xffff0000, v122
	v_lshlrev_b32_e32 v122, 16, v123
	v_and_b32_e32 v123, 0xffff0000, v123
	v_pk_mul_f32 v[130:131], v[128:129], v[128:129]
	v_pk_mul_f32 v[132:133], v[122:123], v[122:123]
	v_add_f32_e32 v130, v130, v131
	v_lshlrev_b32_e32 v126, 16, v124
	v_and_b32_e32 v127, 0xffff0000, v124
	v_add_f32_e32 v130, v132, v130
	v_pk_mul_f32 v[134:135], v[126:127], v[126:127]
	v_add_f32_e32 v130, v133, v130
	v_lshlrev_b32_e32 v124, 16, v125
	v_and_b32_e32 v125, 0xffff0000, v125
	v_add_f32_e32 v130, v134, v130
	v_pk_mul_f32 v[136:137], v[124:125], v[124:125]
	v_add_f32_e32 v130, v135, v130
	v_add_f32_e32 v130, v136, v130
	v_add_f32_e32 v130, v137, v130
	s_and_saveexec_b64 s[0:1], s[40:41]
	s_xor_b64 s[0:1], exec, s[0:1]
	s_cbranch_execz .LBB0_342
	s_waitcnt lgkmcnt(0)
	s_nop 1
	v_add_f32_dpp v130, v130, v130 quad_perm:[1,0,3,2] row_mask:0xf bank_mask:0xf
	s_nop 1
	v_add_f32_dpp v130, v130, v130 quad_perm:[2,3,0,1] row_mask:0xf bank_mask:0xf
	s_nop 1
	v_add_f32_dpp v130, v130, v130 row_half_mirror row_mask:0xf bank_mask:0xf
	s_nop 1
	v_fmamk_f32 v130, v130, 0x3c800000, v199
	v_mul_f32_e32 v131, 0x4f800000, v130
	v_cmp_gt_f32_e32 vcc, s21, v130
	s_nop 1
	v_cndmask_b32_e32 v130, v130, v131, vcc
	v_sqrt_f32_e32 v131, v130
	s_nop 0
	v_add_u32_e32 v132, -1, v131
	v_add_u32_e32 v133, 1, v131
	v_fma_f32 v134, -v132, v131, v130
	v_fma_f32 v135, -v133, v131, v130
	v_cmp_ge_f32_e64 s[50:51], 0, v134
	s_nop 1
	v_cndmask_b32_e64 v131, v131, v132, s[50:51]
	v_cmp_lt_f32_e64 s[50:51], 0, v135
	s_nop 1
	v_cndmask_b32_e64 v131, v131, v133, s[50:51]
	v_mul_f32_e32 v132, 0x37800000, v131
	v_cndmask_b32_e32 v131, v131, v132, vcc
	v_cmp_class_f32_e32 vcc, v130, v200
	s_nop 1
	v_cndmask_b32_e32 v130, v131, v130, vcc
	v_div_scale_f32 v131, s[22:23], v130, v130, 1.0
	v_rcp_f32_e32 v132, v131
	v_div_scale_f32 v133, vcc, 1.0, v130, 1.0
	v_fma_f32 v134, -v131, v132, 1.0
	v_fmac_f32_e32 v132, v134, v132
	v_mul_f32_e32 v134, v133, v132
	v_fma_f32 v135, -v131, v134, v133
	v_fmac_f32_e32 v134, v135, v132
	v_fma_f32 v131, -v131, v134, v133
	v_div_fmas_f32 v131, v131, v132, v134
	v_div_fixup_f32 v130, v131, v130, 1.0
	v_pk_mul_f32 v[128:129], v[130:131], v[128:129] op_sel_hi:[0,1]
	v_pk_mul_f32 v[122:123], v[130:131], v[122:123] op_sel_hi:[0,1]
	v_pk_mul_f32 v[126:127], v[130:131], v[126:127] op_sel_hi:[0,1]
	v_pk_mul_f32 v[124:125], v[130:131], v[124:125] op_sel_hi:[0,1]
	v_pk_mul_f32 v[128:129], v[38:39], v[128:129]
	v_pk_mul_f32 v[130:131], v[40:41], v[122:123]
	v_pk_mul_f32 v[126:127], v[34:35], v[126:127]
	v_pk_mul_f32 v[132:133], v[36:37], v[124:125]
	v_cvt_pk_bf16_f32 v122, v128, v129
	v_cvt_pk_bf16_f32 v123, v130, v131
	v_cvt_pk_bf16_f32 v124, v126, v127
	v_cvt_pk_bf16_f32 v125, v132, v133
	v_lshl_add_u64 v[126:127], s[6:7], 0, v[0:1]
	global_store_dwordx4 v[126:127], v[122:125], off
.LBB0_342:
	s_andn2_saveexec_b64 s[0:1], s[0:1]
	s_cbranch_execz .LBB0_344
	s_waitcnt lgkmcnt(0)
	s_nop 1
	v_add_f32_dpp v130, v130, v130 quad_perm:[1,0,3,2] row_mask:0xf bank_mask:0xf
	s_nop 1
	v_add_f32_dpp v130, v130, v130 quad_perm:[2,3,0,1] row_mask:0xf bank_mask:0xf
	s_nop 1
	v_add_f32_dpp v130, v130, v130 row_half_mirror row_mask:0xf bank_mask:0xf
	s_nop 1
	v_fmamk_f32 v130, v130, 0x3c800000, v199
	v_mul_f32_e32 v131, 0x4f800000, v130
	v_cmp_gt_f32_e32 vcc, s21, v130
	s_nop 1
	v_cndmask_b32_e32 v130, v130, v131, vcc
	v_sqrt_f32_e32 v131, v130
	s_nop 0
	v_add_u32_e32 v132, -1, v131
	v_add_u32_e32 v133, 1, v131
	v_fma_f32 v134, -v132, v131, v130
	v_fma_f32 v135, -v133, v131, v130
	v_cmp_ge_f32_e64 s[50:51], 0, v134
	s_nop 1
	v_cndmask_b32_e64 v131, v131, v132, s[50:51]
	v_cmp_lt_f32_e64 s[50:51], 0, v135
	s_nop 1
	v_cndmask_b32_e64 v131, v131, v133, s[50:51]
	v_mul_f32_e32 v132, 0x37800000, v131
	v_cndmask_b32_e32 v131, v131, v132, vcc
	v_cmp_class_f32_e32 vcc, v130, v200
	s_nop 1
	v_cndmask_b32_e32 v130, v131, v130, vcc
	v_div_scale_f32 v131, s[22:23], v130, v130, 1.0
	v_rcp_f32_e32 v132, v131
	v_div_scale_f32 v133, vcc, 1.0, v130, 1.0
	v_fma_f32 v134, -v131, v132, 1.0
	v_fmac_f32_e32 v132, v134, v132
	v_mul_f32_e32 v134, v133, v132
	v_fma_f32 v135, -v131, v134, v133
	v_fmac_f32_e32 v134, v135, v132
	v_fma_f32 v131, -v131, v134, v133
	v_div_fmas_f32 v131, v131, v132, v134
	v_div_fixup_f32 v130, v131, v130, 1.0
	v_pk_mul_f32 v[128:129], v[130:131], v[128:129] op_sel_hi:[0,1]
	v_pk_mul_f32 v[122:123], v[130:131], v[122:123] op_sel_hi:[0,1]
	v_pk_mul_f32 v[126:127], v[130:131], v[126:127] op_sel_hi:[0,1]
	v_pk_mul_f32 v[124:125], v[130:131], v[124:125] op_sel_hi:[0,1]
	v_pk_mul_f32 v[128:129], v[30:31], v[128:129]
	v_pk_mul_f32 v[122:123], v[32:33], v[122:123]
	v_pk_mul_f32 v[126:127], v[26:27], v[126:127]
	v_pk_mul_f32 v[124:125], v[28:29], v[124:125]
	v_pk_mul_f32 v[128:129], v[128:129], s[20:21] op_sel_hi:[1,0]
	v_pk_mul_f32 v[130:131], v[122:123], s[20:21] op_sel_hi:[1,0]
	v_pk_mul_f32 v[126:127], v[126:127], s[20:21] op_sel_hi:[1,0]
	v_pk_mul_f32 v[132:133], v[124:125], s[20:21] op_sel_hi:[1,0]
	v_cvt_pk_bf16_f32 v122, v128, v129
	v_cvt_pk_bf16_f32 v123, v130, v131
	v_cvt_pk_bf16_f32 v124, v126, v127
	v_cvt_pk_bf16_f32 v125, v132, v133
	v_lshl_add_u64 v[126:127], s[8:9], 0, v[0:1]
	global_store_dwordx4 v[126:127], v[122:125], off
